# plain in-projection epilogue (10 of 22 column tiles) hand-batched: all staged-tile reads in flight, bf16 pack, 8 stores
# speedup vs baseline: 1.0004x; 1.0004x over previous
.Lip_stgdone:
	v_mov_b32_e32 v26, v138
	s_lshl_b32 s57, s18, 7
	s_cmpk_lt_u32 s18, 0x80
	s_cselect_b64 s[16:17], -1, 0
	s_mov_b64 s[0:1], -1
	s_mov_b32 s2, 0x40000
	s_cmp_gt_u32 s42, 2
	s_waitcnt lgkmcnt(0)
	s_barrier
	s_cbranch_scc0 .LBB0_270
	s_cmp_lg_u32 s42, 3
	s_cbranch_scc0 .LBB0_272
	s_add_i32 s0, s42, -10
	s_cmp_gt_u32 s0, 7
	s_mov_b64 s[0:1], -1
	s_cbranch_scc0 .LBB0_251
	s_lshl_b32 s0, s42, 7
	s_cmp_lt_u32 s42, 10
	s_movk_i32 s1, 0xfe00
	s_cselect_b32 s1, s1, 0xfffffc00
	s_add_i32 s0, s1, s0
	s_lshl_b32 s0, s0, 1
	s_add_u32 s2, s94, 0x3200000
	s_addc_u32 s3, s95, 0
	s_add_u32 s2, s2, s0
	s_addc_u32 s3, s3, 0
	s_mul_i32 s0, s57, 0xe00
	s_add_u32 s2, s2, s0
	s_addc_u32 s3, s3, 0
	v_lshrrev_b32_e32 v64, 4, v138
	v_and_b32_e32 v65, 15, v138
	s_movk_i32 s0, 0x210
	v_mul_lo_u32 v67, v64, s0
	v_lshl_add_u32 v67, v65, 5, v67
	s_movk_i32 s0, 0xe00
	v_mul_lo_u32 v66, v64, s0
	v_lshl_add_u32 v66, v65, 4, v66
	ds_read_b128 v[0:3], v67 offset:0
	ds_read_b128 v[4:7], v67 offset:16
	ds_read_b128 v[8:11], v67 offset:8448
	ds_read_b128 v[12:15], v67 offset:8464
	ds_read_b128 v[16:19], v67 offset:16896
	ds_read_b128 v[20:23], v67 offset:16912
	ds_read_b128 v[24:27], v67 offset:25344
	ds_read_b128 v[28:31], v67 offset:25360
	ds_read_b128 v[32:35], v67 offset:33792
	ds_read_b128 v[36:39], v67 offset:33808
	ds_read_b128 v[40:43], v67 offset:42240
	ds_read_b128 v[44:47], v67 offset:42256
	ds_read_b128 v[48:51], v67 offset:50688
	ds_read_b128 v[52:55], v67 offset:50704
	ds_read_b128 v[56:59], v67 offset:59136
	ds_read_b128 v[60:63], v67 offset:59152
	s_waitcnt lgkmcnt(14)
	v_cvt_pk_bf16_f32 v0, v0, v1
	v_cvt_pk_bf16_f32 v1, v2, v3
	v_cvt_pk_bf16_f32 v2, v4, v5
	v_cvt_pk_bf16_f32 v3, v6, v7
	global_store_dwordx4 v66, v[0:3], s[2:3]
	s_waitcnt lgkmcnt(12)
	v_cvt_pk_bf16_f32 v8, v8, v9
	v_cvt_pk_bf16_f32 v9, v10, v11
	v_cvt_pk_bf16_f32 v10, v12, v13
	v_cvt_pk_bf16_f32 v11, v14, v15
	v_add_u32_e32 v66, 0xe000, v66
	global_store_dwordx4 v66, v[8:11], s[2:3]
	s_waitcnt lgkmcnt(10)
	v_cvt_pk_bf16_f32 v16, v16, v17
	v_cvt_pk_bf16_f32 v17, v18, v19
	v_cvt_pk_bf16_f32 v18, v20, v21
	v_cvt_pk_bf16_f32 v19, v22, v23
	v_add_u32_e32 v66, 0xe000, v66
	global_store_dwordx4 v66, v[16:19], s[2:3]
	s_waitcnt lgkmcnt(8)
	v_cvt_pk_bf16_f32 v24, v24, v25
	v_cvt_pk_bf16_f32 v25, v26, v27
	v_cvt_pk_bf16_f32 v26, v28, v29
	v_cvt_pk_bf16_f32 v27, v30, v31
	v_add_u32_e32 v66, 0xe000, v66
	global_store_dwordx4 v66, v[24:27], s[2:3]
	s_waitcnt lgkmcnt(6)
	v_cvt_pk_bf16_f32 v32, v32, v33
	v_cvt_pk_bf16_f32 v33, v34, v35
	v_cvt_pk_bf16_f32 v34, v36, v37
	v_cvt_pk_bf16_f32 v35, v38, v39
	v_add_u32_e32 v66, 0xe000, v66
	global_store_dwordx4 v66, v[32:35], s[2:3]
	s_waitcnt lgkmcnt(4)
	v_cvt_pk_bf16_f32 v40, v40, v41
	v_cvt_pk_bf16_f32 v41, v42, v43
	v_cvt_pk_bf16_f32 v42, v44, v45
	v_cvt_pk_bf16_f32 v43, v46, v47
	v_add_u32_e32 v66, 0xe000, v66
	global_store_dwordx4 v66, v[40:43], s[2:3]
	s_waitcnt lgkmcnt(2)
	v_cvt_pk_bf16_f32 v48, v48, v49
	v_cvt_pk_bf16_f32 v49, v50, v51
	v_cvt_pk_bf16_f32 v50, v52, v53
	v_cvt_pk_bf16_f32 v51, v54, v55
	v_add_u32_e32 v66, 0xe000, v66
	global_store_dwordx4 v66, v[48:51], s[2:3]
	s_waitcnt lgkmcnt(0)
	v_cvt_pk_bf16_f32 v56, v56, v57
	v_cvt_pk_bf16_f32 v57, v58, v59
	v_cvt_pk_bf16_f32 v58, v60, v61
	v_cvt_pk_bf16_f32 v59, v62, v63
	v_add_u32_e32 v66, 0xe000, v66
	global_store_dwordx4 v66, v[56:59], s[2:3]
	s_mov_b64 s[0:1], 0
